# attention: drop the static s_setprio 1 of waves 4-7 (equal priority), on top of cg-sync removal + P0a loads in flight
# speedup vs baseline: 1.0010x; 1.0010x over previous
;     ...
;   const size_t qrow0 = (size_t)b * SEQ + (size_t)qb * 256 + wid * QBLK;
;   const bf16_t* Vh = V + (size_t)b * NKV * LD + h * 128;
;   {
;     const bf16_t* Kh = K + (size_t)b * NKV * LD + h * 128 + mp * 64;
;     const bf16_t* Qw = Q + (qrow0 + r32) * LD + h * 128 + mp * 64 + hi * 8;
;     float l_reg = 0; f32x16 o[4] = {}; bf16x8 qr[4]; float nz_ = 0.f; asm volatile("" : "+v"(nz_)); f32x16 negm; _Pragma("unroll") for (int r = 0; r < 16; ++r) negm[r] = nz_; asm volatile("" : "+v"(negm));
; #pragma unroll
;     for (int d0 = 0; d0 < 4; ++d0) qr[d0] = __builtin_nontemporal_load(reinterpret_cast<const bf16x8*>(Qw + d0 * 16));
;     ...
;     if (wid >= 4) __builtin_amdgcn_s_setprio(1);
.LBB0_691:
	s_ashr_i32 s0, s2, 8
	v_mov_b32_e32 v1, v160
	s_ashr_i32 s1, s0, 31
	s_lshl_b64 s[14:15], s[0:1], 13
	v_readfirstlane_b32 s4, v1
	s_lshl_b32 s1, s2, 8
	s_ashr_i32 s18, s4, 6
	s_and_b32 s1, s1, 0x1f00
	v_and_b32_e32 v34, 31, v1
	s_lshl_b32 s24, s18, 5
	s_or_b32 s14, s14, s1
	s_ashr_i32 s25, s24, 31
	v_or_b32_e32 v2, s14, v34
	v_mov_b32_e32 v3, s15
	s_lshl_b32 s1, s2, 2
	v_lshl_add_u64 v[2:3], v[2:3], 0, s[24:25]
	s_and_b32 s1, s1, 0x380
	v_lshlrev_b64 v[2:3], 11, v[2:3]
	v_bfe_u32 v0, v1, 5, 1
	v_lshl_add_u64 v[2:3], s[26:27], 0, v[2:3]
	s_lshl_b32 s6, s1, 1
	v_mov_b32_e32 v64, v167
	v_lshl_add_u64 v[2:3], v[2:3], 0, s[6:7]
	v_lshlrev_b32_e32 v168, 4, v0
	v_mov_b32_e32 v169, v167
	v_lshl_add_u64 v[2:3], v[2:3], 0, v[168:169]
	v_mov_b32_e32 v65, v64
	v_mov_b32_e32 v66, v64
	v_mov_b32_e32 v67, v64
	v_mov_b32_e32 v68, v64
	v_mov_b32_e32 v69, v64
	v_mov_b32_e32 v70, v64
	v_mov_b32_e32 v71, v64
	v_mov_b32_e32 v72, v64
	v_mov_b32_e32 v73, v64
	v_mov_b32_e32 v74, v64
	v_mov_b32_e32 v75, v64
	v_mov_b32_e32 v76, v64
	v_mov_b32_e32 v77, v64
	v_mov_b32_e32 v78, v64
	v_mov_b32_e32 v79, v64
	global_load_dwordx4 v[156:159], v[2:3], off nt
	global_load_dwordx4 v[152:155], v[2:3], off offset:32 nt
	global_load_dwordx4 v[148:151], v[2:3], off offset:64 nt
	global_load_dwordx4 v[144:147], v[2:3], off offset:96 nt
	s_cmp_lt_i32 s18, 4
	s_cbranch_scc1 .LBB0_693
	s_setprio 0

; #define SBAR() __builtin_amdgcn_sched_barrier(0)
; __device__ __forceinline__ int crow(int r, int hi) { return (r & 3) + 8 * (r >> 2) + 4 * hi; }
; #define FINA(I, P0, P1) finA<I>(P0, P1, ps0, ps1, cv_, pa0, pa1, pa2, pa3)
;     ...
;     { float ps0 = 0.f, ps1 = 0.f; unsigned cv_[4];
;       FINA(0, pB0, pB1); FINA(1, pB0, pB1); FINA(2, pB0, pB1); FINA(3, pB0, pB1); FINA(4, pB0, pB1); FINA(5, pB0, pB1); FINA(6, pB0, pB1); FINA(7, pB0, pB1);
;       float ps = ps0 + ps1; auto rr = __builtin_amdgcn_permlane32_swap(__float_as_uint(ps), __float_as_uint(ps), false, false);
;       ps = __uint_as_float(rr[0]) + __uint_as_float(rr[1]); l_reg = l_reg * alB + ps; }
;     SBAR();
;     pv_d0(o, vb0 + sc_ * SHM_V, pa0, pa1, pa2, pa3);
;     ...
;     __builtin_amdgcn_s_setprio(0);
;     if (hi == 0) li_l[r32] = l_reg; asm volatile("s_waitcnt lgkmcnt(0)" ::: "memory");
;     float rli[16];
; #pragma unroll
;     for (int r = 0; r < 16; ++r) rli[r] = __builtin_amdgcn_rcpf(li_l[crow(r, hi)]);
.LBB0_714:
	v_add_f32_e32 v64, 0, v128
	v_add_f32_e32 v65, 0, v129
	v_add_f32_e32 v68, v130, v64
	v_add_f32_e32 v69, v131, v65
	v_cvt_pk_bf16_f32 v64, v128, v129
	v_cvt_pk_bf16_f32 v65, v130, v131
	v_cvt_pk_bf16_f32 v66, v132, v133
	v_cvt_pk_bf16_f32 v67, v134, v135
	v_cvt_pk_bf16_f32 v70, v136, v137
	v_add_f32_e32 v68, v132, v68
	v_add_f32_e32 v69, v133, v69
	v_add_f32_e32 v68, v134, v68
	v_add_f32_e32 v69, v135, v69
	v_permlane32_swap_b32_e32 v64, v66
	v_permlane32_swap_b32_e32 v65, v67
	v_cvt_pk_bf16_f32 v71, v138, v139
	v_add_f32_e32 v68, v136, v68
	v_add_f32_e32 v69, v137, v69
	v_add_f32_e32 v68, v138, v68
	v_add_f32_e32 v69, v139, v69
	v_cvt_pk_bf16_f32 v72, v140, v141
	v_cvt_pk_bf16_f32 v73, v142, v143
	v_cvt_pk_bf16_f32 v74, v112, v113
	v_add_f32_e32 v68, v140, v68
	v_add_f32_e32 v69, v141, v69
	v_add_f32_e32 v68, v142, v68
	v_add_f32_e32 v69, v143, v69
	v_permlane32_swap_b32_e32 v70, v72
	v_permlane32_swap_b32_e32 v71, v73
	v_cvt_pk_bf16_f32 v75, v114, v115
	v_add_f32_e32 v68, v112, v68
	v_add_f32_e32 v69, v113, v69
	v_add_f32_e32 v68, v114, v68
	v_add_f32_e32 v69, v115, v69
	v_cvt_pk_bf16_f32 v76, v116, v117
	v_cvt_pk_bf16_f32 v77, v118, v119
	v_cvt_pk_bf16_f32 v78, v120, v121
	v_add_f32_e32 v68, v116, v68
	v_add_f32_e32 v69, v117, v69
	v_add_f32_e32 v68, v118, v68
	v_add_f32_e32 v69, v119, v69
	v_permlane32_swap_b32_e32 v74, v76
	v_permlane32_swap_b32_e32 v75, v77
	v_cvt_pk_bf16_f32 v79, v122, v123
	v_add_f32_e32 v68, v120, v68
	v_add_f32_e32 v69, v121, v69
	v_add_f32_e32 v68, v122, v68
	v_add_f32_e32 v69, v123, v69
	v_cvt_pk_bf16_f32 v80, v124, v125
	v_cvt_pk_bf16_f32 v81, v126, v127
	s_nop 0
	v_add_f32_e32 v68, v124, v68
	v_add_f32_e32 v69, v125, v69
	v_add_f32_e32 v68, v126, v68
	v_add_f32_e32 v69, v127, v69
	v_permlane32_swap_b32_e32 v78, v80
	v_permlane32_swap_b32_e32 v79, v81
	s_nop 0
	v_add_f32_e32 v68, v68, v69
	v_mov_b32_e32 v69, v68
	s_nop 1
	v_permlane32_swap_b32_e32 v68, v69
	s_cmp_lg_u32 0, -1
	s_cselect_b32 s24, 0, 0
	s_add_i32 s24, s24, 0x8000
	v_add_u32_e32 v86, s24, v179
	ds_read_b64_tr_b16 v[82:83], v86 offset:0
	ds_read_b64_tr_b16 v[84:85], v86 offset:0x800
	ds_read_b64_tr_b16 v[92:93], v86 offset:0x1000
	ds_read_b64_tr_b16 v[94:95], v86 offset:0x1800
	ds_read_b64_tr_b16 v[96:97], v86 offset:0x2000
	ds_read_b64_tr_b16 v[98:99], v86 offset:0x2800
	ds_read_b64_tr_b16 v[100:101], v86 offset:0x3000
	ds_read_b64_tr_b16 v[102:103], v86 offset:0x3800
	ds_read_b64_tr_b16 v[104:105], v86 offset:0x200
	ds_read_b64_tr_b16 v[106:107], v86 offset:0xa00
	ds_read_b64_tr_b16 v[108:109], v86 offset:0x1200
	ds_read_b64_tr_b16 v[110:111], v86 offset:0x1a00
	ds_read_b64_tr_b16 v[112:113], v86 offset:0x2200
	ds_read_b64_tr_b16 v[114:115], v86 offset:0x2a00
	ds_read_b64_tr_b16 v[116:117], v86 offset:0x3200
	ds_read_b64_tr_b16 v[118:119], v86 offset:0x3a00
	s_waitcnt lgkmcnt(8)
	s_nop 0
	v_mfma_f32_32x32x16_bf16 v[48:63], v[64:67], v[82:85], v[48:63]
	v_mfma_f32_32x32x16_bf16 v[48:63], v[70:73], v[92:95], v[48:63]
	v_mfma_f32_32x32x16_bf16 v[48:63], v[74:77], v[96:99], v[48:63]
	v_mfma_f32_32x32x16_bf16 v[48:63], v[78:81], v[100:103], v[48:63]
	ds_read_b64_tr_b16 v[82:83], v86 offset:0x400
	ds_read_b64_tr_b16 v[84:85], v86 offset:0xc00
	ds_read_b64_tr_b16 v[92:93], v86 offset:0x1400
	ds_read_b64_tr_b16 v[94:95], v86 offset:0x1c00
	ds_read_b64_tr_b16 v[96:97], v86 offset:0x2400
	ds_read_b64_tr_b16 v[98:99], v86 offset:0x2c00
	ds_read_b64_tr_b16 v[100:101], v86 offset:0x3400
	ds_read_b64_tr_b16 v[102:103], v86 offset:0x3c00
	s_waitcnt lgkmcnt(8)
	v_mfma_f32_32x32x16_bf16 v[32:47], v[64:67], v[104:107], v[32:47]
	v_mfma_f32_32x32x16_bf16 v[32:47], v[70:73], v[108:111], v[32:47]
	v_mfma_f32_32x32x16_bf16 v[32:47], v[74:77], v[112:115], v[32:47]
	v_mfma_f32_32x32x16_bf16 v[32:47], v[78:81], v[116:119], v[32:47]
	ds_read_b64_tr_b16 v[104:105], v86 offset:0x600
	ds_read_b64_tr_b16 v[106:107], v86 offset:0xe00
	ds_read_b64_tr_b16 v[108:109], v86 offset:0x1600
	ds_read_b64_tr_b16 v[110:111], v86 offset:0x1e00
	ds_read_b64_tr_b16 v[112:113], v86 offset:0x2600
	ds_read_b64_tr_b16 v[114:115], v86 offset:0x2e00
	ds_read_b64_tr_b16 v[116:117], v86 offset:0x3600
	ds_read_b64_tr_b16 v[118:119], v86 offset:0x3e00
	s_waitcnt lgkmcnt(8)
	v_mfma_f32_32x32x16_bf16 v[16:31], v[64:67], v[82:85], v[16:31]
	v_mfma_f32_32x32x16_bf16 v[16:31], v[70:73], v[92:95], v[16:31]
	v_mfma_f32_32x32x16_bf16 v[16:31], v[74:77], v[96:99], v[16:31]
	v_mfma_f32_32x32x16_bf16 v[16:31], v[78:81], v[100:103], v[16:31]
	s_waitcnt lgkmcnt(0)
	v_mfma_f32_32x32x16_bf16 v[0:15], v[64:67], v[104:107], v[0:15]
	v_mfma_f32_32x32x16_bf16 v[0:15], v[70:73], v[108:111], v[0:15]
	v_mfma_f32_32x32x16_bf16 v[0:15], v[74:77], v[112:115], v[0:15]
	v_mfma_f32_32x32x16_bf16 v[0:15], v[78:81], v[116:119], v[0:15]
	s_setprio 0
	s_and_saveexec_b64 s[68:69], s[0:1]
	v_add_f32_e32 v64, v88, v89
	v_fmac_f32_e32 v64, v178, v185
	v_add_f32_e32 v65, v68, v69
	v_fmac_f32_e32 v65, v64, v90
	ds_write_b32 v177, v65
	s_or_b64 exec, exec, s[68:69]
	s_waitcnt lgkmcnt(0)
	v_add_u32_e32 v80, s19, v168
	s_lshl_b32 s0, s18, 13
	ds_read_b128 v[64:67], v80
	s_add_i32 s0, s0, 0
	v_lshl_add_u32 v68, v169, 2, s0
	v_add_u32_e32 v81, 0x12800, v68
	ds_read_b128 v[68:71], v80 offset:32
	s_waitcnt lgkmcnt(1)
;     ...
;     const bf16_t* Kh = K + (size_t)b * NKV * LD + h * 128 + mp * 64;
;     const bf16_t* Qw = Q + (qrow0 + r32) * LD + h * 128 + mp * 64 + hi * 8;
;     float l_reg = 0; f32x16 o[4] = {}; bf16x8 qr[4]; float nz_ = 0.f; asm volatile("" : "+v"(nz_)); f32x16 negm; _Pragma("unroll") for (int r = 0; r < 16; ++r) negm[r] = nz_; asm volatile("" : "+v"(negm));
; #pragma unroll
;     for (int d0 = 0; d0 < 4; ++d0) qr[d0] = __builtin_nontemporal_load(reinterpret_cast<const bf16x8*>(Qw + d0 * 16));
;     ...
;     for (int r = 0; r < 16; ++r) rli[r] = __builtin_amdgcn_rcpf(li_l[crow(r, hi)]);
;     if (mp == 0) {
; #pragma unroll
;       for (int d0 = 0; d0 < 4; ++d0)
; #pragma unroll
;         for (int r = 0; r < 16; r += 2) stash[(d0 * 8 + (r >> 1)) * 64] = cvt_pk_bf16(o[d0][r] * rli[r], o[d0][r + 1] * rli[r + 1]);
;     } else {
;       float ss[16];
; #pragma unroll
;       for (int r = 0; r < 16; ++r) ss[r] = 0.f;
; #pragma unroll
;       for (int d0 = 0; d0 < 4; ++d0)
; #pragma unroll
;         for (int r = 0; r < 16; r += 2) { const unsigned w = stash[(d0 * 8 + (r >> 1)) * 64];
;           const float a0 = bf_lo(w) - lam * (o[d0][r] * rli[r]), a1 = bf_hi(w) - lam * (o[d0][r + 1] * rli[r + 1]);
;           o[d0][r] = a0; o[d0][r + 1] = a1; ss[r] += a0 * a0; ss[r + 1] += a1 * a1; }
; #pragma unroll
;       for (int r = 0; r < 16; ++r) { float s = ss[r];
;         s += __shfl_xor(s, 1); s += __shfl_xor(s, 2); s += __shfl_xor(s, 4); s += __shfl_xor(s, 8); s += __shfl_xor(s, 16);
;         ss[r] = (1.0f - LAM_INIT) / sqrtf(s * (1.0f / 128.0f) + EPS); }
;       bf16_t* stg = (bf16_t*)(lds + OFF_ST) + wid * 4096;
; #pragma unroll
;       for (int d0 = 0; d0 < 4; ++d0) { const float g = subln_g[d0 * 32 + r32];
; #pragma unroll
;         for (int r = 0; r < 16; ++r) { const unsigned w = cvt_pk_bf16(o[d0][r] * ss[r] * g, 0.f);
;           stg[crow(r, hi) * 128 + d0 * 32 + r32] = (bf16_t)(w & 0xffffu); } }
;       asm volatile("s_waitcnt lgkmcnt(0)" ::: "memory");
;       const char* ob = (const char*)(O + qrow0 * LD + h * 128);
;       const unsigned lo = (unsigned)((lane >> 4) * LD + (lane & 15) * 8) * 2u;
; #pragma unroll
;       for (int i = 0; i < 8; ++i) { const u32x4 v = *(const u32x4*)(stg + (i * 4 + (lane >> 4)) * 128 + (lane & 15) * 8); *(u32x4*)((char*)ob + lo) = v; ob += 4 * LD * 2; }
;     }
;     __syncthreads();
	v_rcp_f32_e32 v72, v64
	v_rcp_f32_e32 v73, v65
	v_rcp_f32_e32 v74, v66
	v_rcp_f32_e32 v75, v67
	ds_read_b128 v[64:67], v80 offset:64
	s_waitcnt lgkmcnt(1)
	v_rcp_f32_e32 v76, v68
	v_rcp_f32_e32 v77, v69
	v_rcp_f32_e32 v78, v70
	v_rcp_f32_e32 v79, v71
	ds_read_b128 v[68:71], v80 offset:96
	v_pk_mul_f32 v[48:49], v[48:49], v[72:73]
	s_waitcnt lgkmcnt(1)
	v_rcp_f32_e32 v64, v64
	v_cvt_pk_bf16_f32 v80, v48, v49
	v_pk_mul_f32 v[48:49], v[50:51], v[74:75]
	v_rcp_f32_e32 v65, v65
	v_cvt_pk_bf16_f32 v48, v48, v49
	v_rcp_f32_e32 v66, v66
	v_rcp_f32_e32 v67, v67
	ds_write2st64_b32 v81, v80, v48 offset1:1
	v_pk_mul_f32 v[48:49], v[52:53], v[76:77]
	s_waitcnt lgkmcnt(1)
	v_rcp_f32_e32 v68, v68
	v_cvt_pk_bf16_f32 v50, v48, v49
	v_pk_mul_f32 v[48:49], v[54:55], v[78:79]
	v_rcp_f32_e32 v69, v69
	v_cvt_pk_bf16_f32 v48, v48, v49
	v_rcp_f32_e32 v70, v70
	v_rcp_f32_e32 v71, v71
	ds_write2st64_b32 v81, v50, v48 offset0:2 offset1:3
	v_pk_mul_f32 v[48:49], v[56:57], v[64:65]
	v_pk_mul_f32 v[32:33], v[32:33], v[72:73]
	v_cvt_pk_bf16_f32 v50, v48, v49
	v_pk_mul_f32 v[48:49], v[58:59], v[66:67]
	v_pk_mul_f32 v[16:17], v[16:17], v[72:73]
	v_cvt_pk_bf16_f32 v48, v48, v49
	ds_write2st64_b32 v81, v50, v48 offset0:4 offset1:5
	v_pk_mul_f32 v[48:49], v[60:61], v[68:69]
	v_pk_mul_f32 v[0:1], v[0:1], v[72:73]
	v_cvt_pk_bf16_f32 v50, v48, v49
	v_pk_mul_f32 v[48:49], v[62:63], v[70:71]
	v_mov_b32_e32 v169, v167
	v_cvt_pk_bf16_f32 v48, v48, v49
	ds_write2st64_b32 v81, v50, v48 offset0:6 offset1:7
	v_cvt_pk_bf16_f32 v48, v32, v33
	v_pk_mul_f32 v[32:33], v[34:35], v[74:75]
	s_nop 0
	v_cvt_pk_bf16_f32 v32, v32, v33
	ds_write2st64_b32 v81, v48, v32 offset0:8 offset1:9
	v_pk_mul_f32 v[32:33], v[36:37], v[76:77]
	s_nop 0
	v_cvt_pk_bf16_f32 v34, v32, v33
	v_pk_mul_f32 v[32:33], v[38:39], v[78:79]
	s_nop 0
	v_cvt_pk_bf16_f32 v32, v32, v33
	ds_write2st64_b32 v81, v34, v32 offset0:10 offset1:11
	v_pk_mul_f32 v[32:33], v[40:41], v[64:65]
	s_nop 0
	v_cvt_pk_bf16_f32 v34, v32, v33
	v_pk_mul_f32 v[32:33], v[42:43], v[66:67]
	s_nop 0
	v_cvt_pk_bf16_f32 v32, v32, v33
	ds_write2st64_b32 v81, v34, v32 offset0:12 offset1:13
	v_pk_mul_f32 v[32:33], v[44:45], v[68:69]
	s_nop 0
	v_cvt_pk_bf16_f32 v34, v32, v33
	v_pk_mul_f32 v[32:33], v[46:47], v[70:71]
	s_nop 0
	v_cvt_pk_bf16_f32 v32, v32, v33
	ds_write2st64_b32 v81, v34, v32 offset0:14 offset1:15
	v_cvt_pk_bf16_f32 v32, v16, v17
	v_pk_mul_f32 v[16:17], v[18:19], v[74:75]
	s_nop 0
	v_cvt_pk_bf16_f32 v16, v16, v17
	ds_write2st64_b32 v81, v32, v16 offset0:16 offset1:17
	v_pk_mul_f32 v[16:17], v[20:21], v[76:77]
	s_nop 0
	v_cvt_pk_bf16_f32 v18, v16, v17
	v_pk_mul_f32 v[16:17], v[22:23], v[78:79]
	s_nop 0
	v_cvt_pk_bf16_f32 v16, v16, v17
	ds_write2st64_b32 v81, v18, v16 offset0:18 offset1:19
	v_pk_mul_f32 v[16:17], v[24:25], v[64:65]
	s_nop 0
	v_cvt_pk_bf16_f32 v18, v16, v17
	v_pk_mul_f32 v[16:17], v[26:27], v[66:67]
	s_nop 0
	v_cvt_pk_bf16_f32 v16, v16, v17
	ds_write2st64_b32 v81, v18, v16 offset0:20 offset1:21
	v_pk_mul_f32 v[16:17], v[28:29], v[68:69]
	s_nop 0
	v_cvt_pk_bf16_f32 v18, v16, v17
	v_pk_mul_f32 v[16:17], v[30:31], v[70:71]
	s_nop 0
	v_cvt_pk_bf16_f32 v16, v16, v17
	ds_write2st64_b32 v81, v18, v16 offset0:22 offset1:23
	v_cvt_pk_bf16_f32 v16, v0, v1
	v_pk_mul_f32 v[0:1], v[2:3], v[74:75]
	s_nop 0
	v_cvt_pk_bf16_f32 v0, v0, v1
	ds_write2st64_b32 v81, v16, v0 offset0:24 offset1:25
	v_pk_mul_f32 v[0:1], v[4:5], v[76:77]
	s_nop 0
	v_cvt_pk_bf16_f32 v2, v0, v1
	v_pk_mul_f32 v[0:1], v[6:7], v[78:79]
	s_nop 0
	v_cvt_pk_bf16_f32 v0, v0, v1
	ds_write2st64_b32 v81, v2, v0 offset0:26 offset1:27
	v_pk_mul_f32 v[0:1], v[8:9], v[64:65]
	v_mov_b32_e32 v64, v167
	v_cvt_pk_bf16_f32 v2, v0, v1
	v_pk_mul_f32 v[0:1], v[10:11], v[66:67]
	s_nop 0
	v_cvt_pk_bf16_f32 v0, v0, v1
	ds_write2st64_b32 v81, v2, v0 offset0:28 offset1:29
	v_pk_mul_f32 v[0:1], v[12:13], v[68:69]
	s_nop 0
	v_cvt_pk_bf16_f32 v2, v0, v1
	v_pk_mul_f32 v[0:1], v[14:15], v[70:71]
	s_nop 0
	v_cvt_pk_bf16_f32 v0, v0, v1
	v_mov_b32_e32 v1, v160
	ds_write2st64_b32 v81, v2, v0 offset0:30 offset1:31
	s_waitcnt lgkmcnt(0)
	s_barrier
	s_nop 0
	v_readfirstlane_b32 s0, v1
	s_ashr_i32 s18, s0, 6
	s_lshl_b32 s1, s18, 5
	s_ashr_i32 s19, s1, 31
	s_add_u32 s14, s14, s1
	v_and_b32_e32 v178, 31, v1
	s_addc_u32 s15, s15, s19
	v_or_b32_e32 v2, s14, v178
	v_mov_b32_e32 v3, s15
	v_lshlrev_b64 v[2:3], 11, v[2:3]
	v_bfe_u32 v0, v1, 5, 1
	v_lshl_add_u64 v[2:3], s[26:27], 0, v[2:3]
	v_lshl_add_u64 v[2:3], v[2:3], 0, s[6:7]
	v_lshlrev_b32_e32 v168, 4, v0
	v_lshl_add_u64 v[2:3], v[2:3], 0, v[168:169]
	v_mov_b32_e32 v65, v64
	v_mov_b32_e32 v66, v64
	v_mov_b32_e32 v67, v64
	v_mov_b32_e32 v68, v64
	v_mov_b32_e32 v69, v64
	v_mov_b32_e32 v70, v64
	v_mov_b32_e32 v71, v64
	v_mov_b32_e32 v72, v64
	v_mov_b32_e32 v73, v64
	v_mov_b32_e32 v74, v64
	v_mov_b32_e32 v75, v64
	v_mov_b32_e32 v76, v64
	v_mov_b32_e32 v77, v64
	v_mov_b32_e32 v78, v64
	v_mov_b32_e32 v79, v64
	global_load_dwordx4 v[156:159], v[2:3], off offset:128 nt
	global_load_dwordx4 v[152:155], v[2:3], off offset:160 nt
	global_load_dwordx4 v[148:151], v[2:3], off offset:192 nt
	global_load_dwordx4 v[144:147], v[2:3], off offset:224 nt
	s_cmp_lt_i32 s18, 4
	s_cbranch_scc1 .LBB0_718
	s_setprio 0
